# baseline (speedup 1.0000x reference)
.LBB0_85:
	v_mov_b32_e32 v40, v240
	v_mov_b64_e32 v[0:1], s[64:65]
	v_readfirstlane_b32 s17, v40
	s_ashr_i32 s19, s17, 6
	s_and_b32 s18, s19, 3
	s_lshl_b32 s10, s18, 5
	v_and_b32_e32 v6, 31, v40
	s_add_i32 s10, s10, s5
	v_add_u32_e32 v194, s10, v6
	s_movk_i32 s5, 0x5800
	s_lshl_b32 s3, s3, 7
	s_ashr_i32 s20, s17, 8
	v_mad_i64_i32 v[196:197], s[10:11], v194, s5, v[0:1]
	s_and_b32 s3, s3, 0x380
	s_lshl_b32 s90, s3, 1
	s_lshl_b32 s10, s20, 6
	v_bfe_u32 v41, v40, 5, 1
	v_lshl_add_u64 v[2:3], v[196:197], 0, s[90:91]
	s_ashr_i32 s11, s10, 31
	v_lshl_add_u64 v[2:3], s[10:11], 1, v[2:3]
	v_lshlrev_b32_e32 v128, 4, v41
	v_lshl_add_u64 v[2:3], v[2:3], 0, v[128:129]
	global_load_dwordx4 v[130:133], v[2:3], off
	global_load_dwordx4 v[134:137], v[2:3], off offset:32
	global_load_dwordx4 v[138:141], v[2:3], off offset:64
	global_load_dwordx4 v[142:145], v[2:3], off offset:96
	v_bfe_u32 v2, v40, 3, 3
	v_lshl_or_b32 v2, s19, 3, v2
	v_mad_i64_i32 v[0:1], s[10:11], v2, s5, v[0:1]
	v_lshrrev_b32_e32 v3, 1, v2
	s_and_b32 s10, s19, 1
	v_bfe_u32 v2, v40, 2, 4
	v_lshlrev_b32_e32 v6, 7, v6
	v_lshl_or_b32 v2, s10, 5, v2
	v_lshl_or_b32 v43, s20, 13, v6
	v_lshrrev_b32_e32 v6, 1, v40
	v_xor_b32_e32 v7, v3, v40
	v_mul_u32_u24_e32 v2, 0x2c00, v2
	v_bitop3_b32 v6, v41, v6, 7 bitop3:0x78
	v_lshlrev_b32_e32 v128, 1, v2
	v_lshlrev_b32_e32 v4, 3, v40
	v_lshl_or_b32 v204, v6, 4, v43
	v_lshlrev_b32_e32 v6, 4, v7
	s_ashr_i32 s11, s17, 7
	v_lshl_add_u64 v[2:3], s[64:65], 0, v[128:129]
	v_and_b32_e32 v42, 24, v4
	v_lshl_add_u64 v[0:1], v[0:1], 0, s[90:91]
	v_and_b32_e32 v128, 0x70, v6
	v_lshl_or_b32 v4, s11, 5, v42
	s_lshl_b32 s5, s19, 10
	s_lshl_b32 s10, s10, 11
	s_lshl_b32 s11, s11, 12
	v_lshl_add_u64 v[198:199], v[0:1], 0, v[128:129]
	v_lshl_add_u64 v[0:1], v[198:199], 0, s[72:73]
	s_or_b32 s24, s10, s11
	s_add_i32 s19, s5, 0
	s_mov_b32 s10, m0
	s_mov_b32 m0, s19
	s_nop 0
	global_load_lds_dwordx4 v[0:1], off
	s_mov_b32 m0, s10
	v_lshl_add_u64 v[0:1], v[198:199], 0, s[94:95]
	s_add_i32 s21, s19, 0x2000
	s_mov_b32 s10, m0
	s_mov_b32 m0, s21
	s_nop 0
	global_load_lds_dwordx4 v[0:1], off
	s_mov_b32 m0, s10
	s_mov_b64 s[10:11], 0x160800
	v_lshl_add_u64 v[0:1], v[198:199], 0, s[10:11]
	s_add_i32 s10, s19, 0x4000
	s_mov_b32 s11, m0
	s_mov_b32 m0, s10
	s_nop 0
	global_load_lds_dwordx4 v[0:1], off
	s_mov_b32 m0, s11
	s_mov_b64 s[10:11], 0x160880
	v_lshl_add_u64 v[0:1], v[198:199], 0, s[10:11]
	s_add_i32 s10, s19, 0x6000
	s_mov_b32 s11, m0
	s_mov_b32 m0, s10
	s_nop 0
	global_load_lds_dwordx4 v[0:1], off
	s_mov_b32 m0, s11
	s_mov_b64 s[10:11], 0x2c0800
	v_lshl_add_u64 v[0:1], v[198:199], 0, s[10:11]
	s_add_i32 s10, s19, 0x8000
	s_mov_b32 s11, m0
	s_mov_b32 m0, s10
	s_nop 0
	global_load_lds_dwordx4 v[0:1], off
	s_mov_b32 m0, s11
	v_ashrrev_i32_e32 v5, 31, v4
	v_lshl_add_u64 v[2:3], v[2:3], 0, s[90:91]
	s_mov_b64 s[10:11], 0x2c0880
	v_lshl_add_u64 v[2:3], v[4:5], 1, v[2:3]
	v_lshl_add_u64 v[0:1], v[198:199], 0, s[10:11]
	s_add_i32 s10, s19, 0xa000
	s_mov_b32 s11, m0
	s_mov_b32 m0, s10
	s_nop 0
	global_load_lds_dwordx4 v[0:1], off
	s_mov_b32 m0, s11
	s_add_i32 s20, s24, 0
	v_lshl_add_u64 v[200:201], v[2:3], 0, s[98:99]
	s_add_i32 s10, s20, 0x10000
	s_mov_b32 s11, m0
	s_mov_b32 m0, s10
	s_nop 0
	global_load_lds_dwordx4 v[200:201], off
	s_mov_b32 m0, s11
	s_mov_b64 s[10:11], 0x59000
	v_lshl_add_u64 v[0:1], v[2:3], 0, s[10:11]
	s_add_i32 s10, s20, 0x10400
	s_mov_b32 s11, m0
	s_mov_b32 m0, s10
	s_nop 0
	global_load_lds_dwordx4 v[0:1], off
	s_mov_b32 m0, s11
	s_mov_b64 s[10:11], 0x161000
	v_lshl_add_u64 v[0:1], v[2:3], 0, s[10:11]
	s_add_i32 s10, s20, 0x14000
	s_mov_b32 s11, m0
	s_mov_b32 m0, s10
	s_nop 0
	global_load_lds_dwordx4 v[0:1], off
	s_mov_b32 m0, s11
	s_mov_b64 s[10:11], 0x1b9000
	v_lshl_add_u64 v[0:1], v[2:3], 0, s[10:11]
	s_add_i32 s20, s20, 0x14400
	s_mov_b32 s10, m0
	s_mov_b32 m0, s20
	s_nop 0
	global_load_lds_dwordx4 v[0:1], off
	s_mov_b32 m0, s10
	s_waitcnt vmcnt(0)
	s_barrier
	v_add_u32_e32 v44, 0, v204
	ds_read_b128 v[0:3], v44
	ds_read_b128 v[4:7], v44 offset:4096
	s_waitcnt vmcnt(3) lgkmcnt(1)
	v_mfma_f32_32x32x16_bf16 v[16:31], v[0:3], v[130:133], 0
	v_bfe_u32 v45, v40, 1, 3
	v_bitop3_b32 v0, v41, v45, 2 bitop3:0x36
	v_lshl_or_b32 v128, v0, 4, v43
	v_add_u32_e32 v46, 0, v128
	ds_read_b128 v[32:35], v46
	ds_read_b128 v[36:39], v46 offset:4096
	v_lshlrev_b32_e32 v203, 2, v41
	s_mov_b64 s[22:23], 0x420800
	s_waitcnt lgkmcnt(2)
	v_mfma_f32_32x32x16_bf16 v[0:15], v[4:7], v[130:133], 0
	v_mov_b32_e32 v209, 0
	v_and_b32_e32 v202, 63, v40
	v_ashrrev_i32_e32 v195, 31, v194
	s_movk_i32 s10, 0x4000
	s_mov_b32 s11, 0x8000
	s_mov_b32 s20, 0
	s_mov_b32 s33, 0
	s_waitcnt vmcnt(2) lgkmcnt(1)
	v_mfma_f32_32x32x16_bf16 v[16:31], v[32:35], v[134:137], v[16:31]
	v_bitop3_b32 v32, v41, v45, 4 bitop3:0x36
	v_lshl_or_b32 v205, v32, 4, v43
	v_add_u32_e32 v47, 0, v205
	v_mov_b32_e32 v48, 0
	v_mov_b32_e32 v49, v209
	v_mov_b32_e32 v50, v209
	v_mov_b32_e32 v51, v209
	s_waitcnt lgkmcnt(0)
	v_mfma_f32_32x32x16_bf16 v[0:15], v[36:39], v[134:137], v[0:15]
	ds_read_b128 v[32:35], v47
	ds_read_b128 v[36:39], v47 offset:4096
	v_mov_b32_e32 v52, v209
	v_mov_b32_e32 v53, v209
	v_mov_b32_e32 v54, v209
	v_mov_b32_e32 v55, v209
	v_mov_b32_e32 v56, v209
	v_mov_b32_e32 v57, v209
	s_waitcnt vmcnt(1) lgkmcnt(1)
	v_mfma_f32_32x32x16_bf16 v[16:31], v[32:35], v[138:141], v[16:31]
	v_bitop3_b32 v32, v41, v45, 6 bitop3:0x36
	v_lshl_or_b32 v206, v32, 4, v43
	v_add_u32_e32 v43, 0, v206
	ds_read_b128 v[32:35], v43
	v_mov_b32_e32 v45, v209
	v_mov_b32_e32 v58, v209
	v_mov_b32_e32 v59, v209
	s_waitcnt lgkmcnt(1)
	v_mfma_f32_32x32x16_bf16 v[0:15], v[36:39], v[138:141], v[0:15]
	v_lshrrev_b32_e32 v36, 2, v40
	v_and_or_b32 v41, v36, 3, v203
	ds_read_b128 v[36:39], v43 offset:4096
	ds_read_b128 v[100:103], v44 offset:16384
	ds_read_b128 v[96:99], v44 offset:20480
	ds_read_b128 v[182:185], v46 offset:16384
	ds_read_b128 v[178:181], v46 offset:20480
	ds_read_b128 v[174:177], v47 offset:16384
	ds_read_b128 v[170:173], v47 offset:20480
	ds_read_b128 v[166:169], v43 offset:16384
	ds_read_b128 v[162:165], v43 offset:20480
	s_waitcnt lgkmcnt(0)
	s_barrier
	v_mov_b32_e32 v43, v209
	v_mov_b32_e32 v44, v209
	s_waitcnt vmcnt(0) lgkmcnt(9)
	v_mfma_f32_32x32x16_bf16 v[16:31], v[32:35], v[142:145], v[16:31]
	v_lshlrev_b32_e32 v33, 1, v40
	v_lshlrev_b32_e32 v32, 6, v41
	v_and_b32_e32 v33, 32, v33
	v_or3_b32 v207, v32, v33, v42
	v_lshl_add_u64 v[32:33], v[198:199], 0, s[22:23]
	s_mov_b32 s22, m0
	s_add_i32 m0, s19, 0xc000
	s_nop 0
	global_load_lds_dwordx4 v[32:33], off
	s_mov_b32 m0, s22
	s_mov_b64 s[22:23], 0x420880
	s_waitcnt lgkmcnt(8)
	v_mfma_f32_32x32x16_bf16 v[0:15], v[36:39], v[142:145], v[0:15]
	s_nop 3
	v_exp_f32_e32 v80, v16
	v_exp_f32_e32 v81, v17
	v_exp_f32_e32 v82, v18
	v_exp_f32_e32 v83, v19
	v_exp_f32_e32 v84, v20
	v_exp_f32_e32 v85, v21
	v_exp_f32_e32 v86, v22
	v_exp_f32_e32 v87, v23
	v_exp_f32_e32 v88, v24
	v_exp_f32_e32 v89, v25
	v_exp_f32_e32 v90, v26
	v_exp_f32_e32 v91, v27
	v_exp_f32_e32 v92, v28
	v_exp_f32_e32 v93, v29
	v_exp_f32_e32 v94, v30
	v_exp_f32_e32 v95, v31
	v_exp_f32_e32 v64, v0
	v_exp_f32_e32 v65, v1
	v_exp_f32_e32 v66, v2
	v_exp_f32_e32 v67, v3
	v_exp_f32_e32 v68, v4
	v_exp_f32_e32 v69, v5
	v_exp_f32_e32 v70, v6
	v_exp_f32_e32 v71, v7
	v_exp_f32_e32 v72, v8
	v_exp_f32_e32 v73, v9
	v_exp_f32_e32 v74, v10
	v_exp_f32_e32 v75, v11
	v_exp_f32_e32 v76, v12
	v_exp_f32_e32 v77, v13
	v_exp_f32_e32 v78, v14
	v_exp_f32_e32 v79, v15
	v_lshl_add_u64 v[32:33], v[198:199], 0, s[22:23]
	s_mov_b32 s19, m0
	s_add_i32 m0, s21, 0xc000
	s_nop 0
	global_load_lds_dwordx4 v[32:33], off
	s_mov_b32 m0, s19
	v_add_u32_e32 v208, 0, v207
	s_add_i32 s19, s4, -1
	s_add_i32 s21, s5, 0x2000
	s_add_i32 s22, s24, 0x10000
	v_mov_b32_e32 v0, 0
	v_mov_b32_e32 v1, v209
	v_mov_b32_e32 v2, v209
	v_mov_b32_e32 v3, v209
	v_mov_b32_e32 v4, v209
	v_mov_b32_e32 v5, v209
	v_mov_b32_e32 v6, v209
	v_mov_b32_e32 v7, v209
	v_mov_b32_e32 v8, v209
	v_mov_b32_e32 v9, v209
	v_mov_b32_e32 v10, v209
	v_mov_b32_e32 v11, v209
	v_mov_b32_e32 v12, v209
	v_mov_b32_e32 v13, v209
	v_mov_b32_e32 v14, v209
	v_mov_b32_e32 v15, v209
	v_mov_b32_e32 v16, 0
	v_mov_b32_e32 v17, v209
	v_mov_b32_e32 v18, v209
	v_mov_b32_e32 v19, v209
	v_mov_b32_e32 v20, v209
	v_mov_b32_e32 v21, v209
	v_mov_b32_e32 v22, v209
	v_mov_b32_e32 v23, v209
	v_mov_b32_e32 v24, v209
	v_mov_b32_e32 v25, v209
	v_mov_b32_e32 v26, v209
	v_mov_b32_e32 v27, v209
	v_mov_b32_e32 v28, v209
	v_mov_b32_e32 v29, v209
	v_mov_b32_e32 v30, v209
	v_mov_b32_e32 v31, v209
	v_mov_b32_e32 v32, 0
	v_mov_b32_e32 v33, v209
	v_mov_b32_e32 v34, v209
	v_mov_b32_e32 v35, v209
	v_mov_b32_e32 v36, v209
	v_mov_b32_e32 v37, v209
	v_mov_b32_e32 v38, v209
	v_mov_b32_e32 v39, v209
	v_mov_b32_e32 v40, v209
	v_mov_b32_e32 v41, v209
	v_mov_b32_e32 v42, v209
	v_mov_b32_e32 v46, v209
	v_mov_b32_e32 v47, v209
	v_mov_b32_e32 v60, v209
	v_mov_b32_e32 v61, v209
	v_mov_b32_e32 v62, v209
	v_mov_b32_e32 v63, v209
	v_readfirstlane_b32 s44, v198
	v_readfirstlane_b32 s45, v199
	s_nop 1
	s_sub_u32 s44, s44, 0x200000
	s_subb_u32 s45, s45, 0
	s_add_i32 s32, s21, 0xffffff80
	v_subrev_u32_e32 v199, s44, v198
	v_add_u32_e32 v199, 0x800, v199
	v_subrev_u32_e32 v201, s44, v200
	s_min_u32 s90, s19, 4
	s_mul_i32 s90, s90, 0x160000
	s_add_i32 m0, s5, 0
	s_add_u32 s100, s44, s90
	s_addc_u32 s101, s45, 0
	global_load_lds_dwordx4 v199, s[100:101]
	s_add_i32 m0, s32, 0
	s_nop 0
	global_load_lds_dwordx4 v199, s[100:101] offset:128
	s_mov_b32 s90, 0x2c0000
	s_add_i32 m0, s22, 0x8000
	s_add_u32 s100, s44, s90
	s_addc_u32 s101, s45, 0
	global_load_lds_dwordx4 v201, s[100:101]
	s_add_i32 m0, s22, 0x8400
	s_add_u32 s100, s100, 0x58000
	s_addc_u32 s101, s101, 0
	global_load_lds_dwordx4 v201, s[100:101]
	v_add_u32_e32 v207, 0x10000, v207
	s_mul_i32 s23, s19, 0x160000
	s_mov_b32 s10, 0x6e0000
	s_mov_b32 s11, 0x420000
.LBB0_86:
	s_add_i32 s24, s33, 2
	v_mfma_f32_32x32x16_bf16 v[112:127], v[100:103], v[130:133], 0
	v_add_f32_e32 v100, v82, v80
	v_add_f32_e32 v101, v83, v81
	v_cvt_pk_bf16_f32 v158, v80, v81
	v_cvt_pk_bf16_f32 v159, v82, v83
	v_add_f32_e32 v80, v84, v100
	v_add_f32_e32 v81, v85, v101
	v_add_f32_e32 v146, v86, v80
	v_cvt_pk_bf16_f32 v160, v84, v85
	v_mfma_f32_32x32x16_bf16 v[96:111], v[96:99], v[130:133], 0
	v_add_f32_e32 v84, v87, v81
	v_cvt_pk_bf16_f32 v161, v86, v87
	ds_read_b64_tr_b16 v[80:81], v207
	ds_read_b64_tr_b16 v[82:83], v207 offset:512
	v_add_f32_e32 v85, v88, v146
	v_add_f32_e32 v84, v89, v84
	v_mfma_f32_32x32x16_bf16 v[112:127], v[182:185], v[134:137], v[112:127]
	v_add_f32_e32 v146, v90, v85
	v_add_f32_e32 v147, v91, v84
	v_cvt_pk_bf16_f32 v154, v88, v89
	v_cvt_pk_bf16_f32 v155, v90, v91
	ds_read_b64_tr_b16 v[84:85], v207 offset:4096
	ds_read_b64_tr_b16 v[86:87], v207 offset:4608
	v_add_f32_e32 v88, v92, v146
	v_add_f32_e32 v89, v93, v147
	v_mfma_f32_32x32x16_bf16 v[96:111], v[178:181], v[134:137], v[96:111]
	v_add_f32_e32 v146, v94, v88
	v_add_f32_e32 v147, v95, v89
	v_cvt_pk_bf16_f32 v156, v92, v93
	v_cvt_pk_bf16_f32 v157, v94, v95
	ds_read_b64_tr_b16 v[88:89], v207 offset:8192
	ds_read_b64_tr_b16 v[90:91], v207 offset:8704
	v_add_f32_e32 v92, v64, v146
	v_add_f32_e32 v93, v65, v147
	v_mfma_f32_32x32x16_bf16 v[112:127], v[174:177], v[138:141], v[112:127]
	v_add_f32_e32 v92, v66, v92
	v_add_f32_e32 v93, v67, v93
	v_cvt_pk_bf16_f32 v150, v64, v65
	v_cvt_pk_bf16_f32 v151, v66, v67
	ds_read_b64_tr_b16 v[64:65], v207 offset:12288
	ds_read_b64_tr_b16 v[66:67], v207 offset:12800
	v_add_f32_e32 v92, v68, v92
	v_add_f32_e32 v93, v69, v93
	v_mfma_f32_32x32x16_bf16 v[96:111], v[170:173], v[138:141], v[96:111]
	s_min_u32 s90, s10, s23
	s_add_i32 s10, s10, 0x160000
	s_add_i32 m0, s5, 0x4000
	s_add_u32 s100, s44, s90
	s_addc_u32 s101, s45, 0
	global_load_lds_dwordx4 v199, s[100:101]
	v_add_f32_e32 v92, v70, v92
	v_add_f32_e32 v93, v71, v93
	v_cvt_pk_bf16_f32 v152, v68, v69
	v_cvt_pk_bf16_f32 v153, v70, v71
	v_add_f32_e32 v68, v72, v92
	v_add_f32_e32 v69, v73, v93
	v_mfma_f32_32x32x16_bf16 v[112:127], v[166:169], v[142:145], v[112:127]
	s_add_i32 m0, s32, 0x4000
	s_nop 0
	global_load_lds_dwordx4 v199, s[100:101] offset:128
	v_add_f32_e32 v68, v74, v68
	v_add_f32_e32 v69, v75, v69
	v_cvt_pk_bf16_f32 v146, v72, v73
	v_cvt_pk_bf16_f32 v147, v74, v75
	v_add_f32_e32 v68, v76, v68
	v_add_f32_e32 v69, v77, v69
	v_mfma_f32_32x32x16_bf16 v[96:111], v[162:165], v[142:145], v[96:111]
	s_min_u32 s90, s11, s23
	s_add_i32 s11, s11, 0x160000
	s_add_i32 m0, s22, 0xc000
	s_add_u32 s100, s44, s90
	s_addc_u32 s101, s45, 0
	global_load_lds_dwordx4 v201, s[100:101]
	v_add_f32_e32 v68, v78, v68
	v_add_f32_e32 v69, v79, v69
	v_cvt_pk_bf16_f32 v148, v76, v77
	v_cvt_pk_bf16_f32 v149, v78, v79
	s_nop 0
	v_exp_f32_e32 v112, v112
	v_exp_f32_e32 v113, v113
	s_waitcnt lgkmcnt(4)
	v_mfma_f32_32x32x16_bf16 v[48:63], v[80:83], v[158:161], v[48:63]
	v_add_f32_e32 v92, v68, v69
	ds_read_b64_tr_b16 v[68:69], v207 offset:1024
	ds_read_b64_tr_b16 v[70:71], v207 offset:1536
	v_exp_f32_e32 v114, v114
	v_exp_f32_e32 v115, v115
	v_mfma_f32_32x32x16_bf16 v[32:47], v[84:87], v[158:161], v[32:47]
	ds_read_b64_tr_b16 v[72:73], v207 offset:5120
	ds_read_b64_tr_b16 v[74:75], v207 offset:5632
	v_exp_f32_e32 v116, v116
	v_exp_f32_e32 v117, v117
	s_waitcnt lgkmcnt(4)
	v_mfma_f32_32x32x16_bf16 v[16:31], v[88:91], v[158:161], v[16:31]
	ds_read_b64_tr_b16 v[76:77], v207 offset:9216
	ds_read_b64_tr_b16 v[78:79], v207 offset:9728
	v_exp_f32_e32 v118, v118
	v_exp_f32_e32 v119, v119
	v_mfma_f32_32x32x16_bf16 v[0:15], v[64:67], v[158:161], v[0:15]
	ds_read_b64_tr_b16 v[80:81], v207 offset:13312
	ds_read_b64_tr_b16 v[82:83], v207 offset:13824
	v_exp_f32_e32 v120, v120
	v_exp_f32_e32 v121, v121
	s_waitcnt lgkmcnt(4)
	v_mfma_f32_32x32x16_bf16 v[48:63], v[68:71], v[154:157], v[48:63]
	ds_read_b64_tr_b16 v[84:85], v207 offset:2048
	ds_read_b64_tr_b16 v[86:87], v207 offset:2560
	ds_read_b128 v[68:71], v204 offset:32768
	v_exp_f32_e32 v122, v122
	v_exp_f32_e32 v123, v123
	v_mfma_f32_32x32x16_bf16 v[32:47], v[72:75], v[154:157], v[32:47]
	ds_read_b64_tr_b16 v[72:73], v207 offset:6144
	ds_read_b64_tr_b16 v[74:75], v207 offset:6656
	ds_read_b128 v[64:67], v204 offset:36864
	v_exp_f32_e32 v124, v124
	v_exp_f32_e32 v125, v125
	s_waitcnt lgkmcnt(6)
	v_mfma_f32_32x32x16_bf16 v[16:31], v[76:79], v[154:157], v[16:31]
	ds_read_b64_tr_b16 v[76:77], v207 offset:10240
	ds_read_b64_tr_b16 v[78:79], v207 offset:10752
	ds_read_b128 v[182:185], v128 offset:32768
	v_exp_f32_e32 v126, v126
	v_exp_f32_e32 v127, v127
	v_mfma_f32_32x32x16_bf16 v[0:15], v[80:83], v[154:157], v[0:15]
	ds_read_b64_tr_b16 v[80:81], v207 offset:14336
	ds_read_b64_tr_b16 v[82:83], v207 offset:14848
	ds_read_b128 v[178:181], v128 offset:36864
	v_exp_f32_e32 v96, v96
	v_exp_f32_e32 v97, v97
	s_waitcnt lgkmcnt(7)
	v_mfma_f32_32x32x16_bf16 v[48:63], v[84:87], v[150:153], v[48:63]
	ds_read_b64_tr_b16 v[84:85], v207 offset:3072
	ds_read_b64_tr_b16 v[86:87], v207 offset:3584
	ds_read_b128 v[174:177], v205 offset:32768
	v_exp_f32_e32 v98, v98
	v_exp_f32_e32 v99, v99
	v_mfma_f32_32x32x16_bf16 v[32:47], v[72:75], v[150:153], v[32:47]
	ds_read_b64_tr_b16 v[72:73], v207 offset:7168
	ds_read_b64_tr_b16 v[74:75], v207 offset:7680
	ds_read_b128 v[170:173], v205 offset:36864
	v_exp_f32_e32 v100, v100
	v_exp_f32_e32 v101, v101
	s_waitcnt lgkmcnt(7)
	v_mfma_f32_32x32x16_bf16 v[16:31], v[76:79], v[150:153], v[16:31]
	ds_read_b64_tr_b16 v[76:77], v207 offset:11264
	ds_read_b64_tr_b16 v[78:79], v207 offset:11776
	ds_read_b128 v[166:169], v206 offset:32768
	v_exp_f32_e32 v102, v102
	v_exp_f32_e32 v103, v103
	v_mfma_f32_32x32x16_bf16 v[0:15], v[80:83], v[150:153], v[0:15]
	ds_read_b64_tr_b16 v[80:81], v207 offset:15360
	ds_read_b64_tr_b16 v[82:83], v207 offset:15872
	ds_read_b128 v[162:165], v206 offset:36864
	v_exp_f32_e32 v104, v104
	v_exp_f32_e32 v105, v105
	s_waitcnt lgkmcnt(7)
	v_mfma_f32_32x32x16_bf16 v[48:63], v[84:87], v[146:149], v[48:63]
	s_add_i32 m0, s22, 0xc000
	s_addk_i32 m0, 0x400
	s_add_u32 s100, s100, 0x58000
	s_addc_u32 s101, s101, 0
	global_load_lds_dwordx4 v201, s[100:101]
	v_exp_f32_e32 v106, v106
	v_exp_f32_e32 v107, v107
	v_mfma_f32_32x32x16_bf16 v[32:47], v[72:75], v[146:149], v[32:47]
	v_exp_f32_e32 v108, v108
	v_exp_f32_e32 v109, v109
	s_waitcnt lgkmcnt(1)
	v_mfma_f32_32x32x16_bf16 v[16:31], v[76:79], v[146:149], v[16:31]
	v_exp_f32_e32 v110, v110
	v_exp_f32_e32 v111, v111
	v_mfma_f32_32x32x16_bf16 v[0:15], v[80:83], v[146:149], v[0:15]
	s_waitcnt vmcnt(8) lgkmcnt(0)
	s_barrier
	v_add_f32_e32 v186, v209, v92
	v_mfma_f32_32x32x16_bf16 v[80:95], v[68:71], v[130:133], 0
	v_add_f32_e32 v68, v114, v112
	v_add_f32_e32 v69, v115, v113
	v_cvt_pk_bf16_f32 v158, v112, v113
	v_cvt_pk_bf16_f32 v159, v114, v115
	v_add_f32_e32 v68, v116, v68
	v_add_f32_e32 v112, v117, v69
	v_add_f32_e32 v146, v118, v68
	v_cvt_pk_bf16_f32 v160, v116, v117
	v_mfma_f32_32x32x16_bf16 v[64:79], v[64:67], v[130:133], 0
	v_add_f32_e32 v116, v119, v112
	v_cvt_pk_bf16_f32 v161, v118, v119
	ds_read_b64_tr_b16 v[112:113], v207 offset:16384
	ds_read_b64_tr_b16 v[114:115], v207 offset:16896
	v_add_f32_e32 v117, v120, v146
	v_add_f32_e32 v116, v121, v116
	v_mfma_f32_32x32x16_bf16 v[80:95], v[182:185], v[134:137], v[80:95]
	v_add_f32_e32 v146, v122, v117
	v_add_f32_e32 v147, v123, v116
	v_cvt_pk_bf16_f32 v154, v120, v121
	v_cvt_pk_bf16_f32 v155, v122, v123
	ds_read_b64_tr_b16 v[116:117], v207 offset:20480
	ds_read_b64_tr_b16 v[118:119], v207 offset:20992
	v_add_f32_e32 v120, v124, v146
	v_add_f32_e32 v121, v125, v147
	v_mfma_f32_32x32x16_bf16 v[64:79], v[178:181], v[134:137], v[64:79]
	v_add_f32_e32 v146, v126, v120
	v_add_f32_e32 v147, v127, v121
	v_cvt_pk_bf16_f32 v156, v124, v125
	v_cvt_pk_bf16_f32 v157, v126, v127
	ds_read_b64_tr_b16 v[120:121], v207 offset:24576
	ds_read_b64_tr_b16 v[122:123], v207 offset:25088
	v_add_f32_e32 v124, v96, v146
	v_add_f32_e32 v125, v97, v147
	v_mfma_f32_32x32x16_bf16 v[80:95], v[174:177], v[138:141], v[80:95]
	v_add_f32_e32 v124, v98, v124
	v_add_f32_e32 v125, v99, v125
	v_cvt_pk_bf16_f32 v150, v96, v97
	v_cvt_pk_bf16_f32 v151, v98, v99
	ds_read_b64_tr_b16 v[96:97], v207 offset:28672
	ds_read_b64_tr_b16 v[98:99], v207 offset:29184
	v_add_f32_e32 v124, v100, v124
	v_add_f32_e32 v125, v101, v125
	v_mfma_f32_32x32x16_bf16 v[64:79], v[170:173], v[138:141], v[64:79]
	s_min_u32 s90, s10, s23
	s_add_i32 s10, s10, 0x160000
	s_add_i32 m0, s5, 0x8000
	s_add_u32 s100, s44, s90
	s_addc_u32 s101, s45, 0
	global_load_lds_dwordx4 v199, s[100:101]
	v_add_f32_e32 v124, v102, v124
	v_add_f32_e32 v125, v103, v125
	v_cvt_pk_bf16_f32 v152, v100, v101
	v_cvt_pk_bf16_f32 v153, v102, v103
	v_add_f32_e32 v100, v104, v124
	v_add_f32_e32 v101, v105, v125
	v_mfma_f32_32x32x16_bf16 v[80:95], v[166:169], v[142:145], v[80:95]
	s_add_i32 m0, s32, 0x8000
	s_nop 0
	global_load_lds_dwordx4 v199, s[100:101] offset:128
	v_add_f32_e32 v100, v106, v100
	v_add_f32_e32 v101, v107, v101
	v_cvt_pk_bf16_f32 v146, v104, v105
	v_cvt_pk_bf16_f32 v147, v106, v107
	v_add_f32_e32 v100, v108, v100
	v_add_f32_e32 v101, v109, v101
	v_mfma_f32_32x32x16_bf16 v[64:79], v[162:165], v[142:145], v[64:79]
	s_min_u32 s90, s11, s23
	s_add_i32 s11, s11, 0x160000
	s_add_i32 m0, s22, 0x0
	s_add_u32 s100, s44, s90
	s_addc_u32 s101, s45, 0
	global_load_lds_dwordx4 v201, s[100:101]
	v_add_f32_e32 v100, v110, v100
	v_add_f32_e32 v101, v111, v101
	v_cvt_pk_bf16_f32 v148, v108, v109
	v_cvt_pk_bf16_f32 v149, v110, v111
	v_add_f32_e32 v100, v100, v101
	v_exp_f32_e32 v80, v80
	v_exp_f32_e32 v81, v81
	s_waitcnt lgkmcnt(4)
	v_mfma_f32_32x32x16_bf16 v[48:63], v[112:115], v[158:161], v[48:63]
	v_add_f32_e32 v209, v186, v100
	ds_read_b64_tr_b16 v[100:101], v207 offset:17408
	ds_read_b64_tr_b16 v[102:103], v207 offset:17920
	v_exp_f32_e32 v82, v82
	v_exp_f32_e32 v83, v83
	v_mfma_f32_32x32x16_bf16 v[32:47], v[116:119], v[158:161], v[32:47]
	ds_read_b64_tr_b16 v[104:105], v207 offset:21504
	ds_read_b64_tr_b16 v[106:107], v207 offset:22016
	v_exp_f32_e32 v84, v84
	v_exp_f32_e32 v85, v85
	s_waitcnt lgkmcnt(4)
	v_mfma_f32_32x32x16_bf16 v[16:31], v[120:123], v[158:161], v[16:31]
	ds_read_b64_tr_b16 v[108:109], v207 offset:25600
	ds_read_b64_tr_b16 v[110:111], v207 offset:26112
	v_exp_f32_e32 v86, v86
	v_exp_f32_e32 v87, v87
	v_mfma_f32_32x32x16_bf16 v[0:15], v[96:99], v[158:161], v[0:15]
	ds_read_b64_tr_b16 v[112:113], v207 offset:29696
	ds_read_b64_tr_b16 v[114:115], v207 offset:30208
	v_exp_f32_e32 v88, v88
	v_exp_f32_e32 v89, v89
	s_waitcnt lgkmcnt(4)
	v_mfma_f32_32x32x16_bf16 v[48:63], v[100:103], v[154:157], v[48:63]
	ds_read_b64_tr_b16 v[116:117], v207 offset:18432
	ds_read_b64_tr_b16 v[118:119], v207 offset:18944
	ds_read_b128 v[100:103], v204 offset:49152
	v_exp_f32_e32 v90, v90
	v_exp_f32_e32 v91, v91
	v_mfma_f32_32x32x16_bf16 v[32:47], v[104:107], v[154:157], v[32:47]
	ds_read_b64_tr_b16 v[104:105], v207 offset:22528
	ds_read_b64_tr_b16 v[106:107], v207 offset:23040
	ds_read_b128 v[96:99], v204 offset:53248
	v_exp_f32_e32 v92, v92
	v_exp_f32_e32 v93, v93
	s_waitcnt lgkmcnt(6)
	v_mfma_f32_32x32x16_bf16 v[16:31], v[108:111], v[154:157], v[16:31]
	ds_read_b64_tr_b16 v[108:109], v207 offset:26624
	ds_read_b64_tr_b16 v[110:111], v207 offset:27136
	ds_read_b128 v[182:185], v128 offset:49152
	v_exp_f32_e32 v94, v94
	v_exp_f32_e32 v95, v95
	v_mfma_f32_32x32x16_bf16 v[0:15], v[112:115], v[154:157], v[0:15]
	ds_read_b64_tr_b16 v[112:113], v207 offset:30720
	ds_read_b64_tr_b16 v[114:115], v207 offset:31232
	ds_read_b128 v[178:181], v128 offset:53248
	v_exp_f32_e32 v64, v64
	v_exp_f32_e32 v65, v65
	s_waitcnt lgkmcnt(7)
	v_mfma_f32_32x32x16_bf16 v[48:63], v[116:119], v[150:153], v[48:63]
	ds_read_b64_tr_b16 v[116:117], v207 offset:19456
	ds_read_b64_tr_b16 v[118:119], v207 offset:19968
	ds_read_b128 v[174:177], v205 offset:49152
	v_exp_f32_e32 v66, v66
	v_exp_f32_e32 v67, v67
	v_mfma_f32_32x32x16_bf16 v[32:47], v[104:107], v[150:153], v[32:47]
	ds_read_b64_tr_b16 v[104:105], v207 offset:23552
	ds_read_b64_tr_b16 v[106:107], v207 offset:24064
	ds_read_b128 v[170:173], v205 offset:53248
	v_exp_f32_e32 v68, v68
	v_exp_f32_e32 v69, v69
	s_waitcnt lgkmcnt(7)
	v_mfma_f32_32x32x16_bf16 v[16:31], v[108:111], v[150:153], v[16:31]
	ds_read_b64_tr_b16 v[108:109], v207 offset:27648
	ds_read_b64_tr_b16 v[110:111], v207 offset:28160
	ds_read_b128 v[166:169], v206 offset:49152
	v_exp_f32_e32 v70, v70
	v_exp_f32_e32 v71, v71
	v_mfma_f32_32x32x16_bf16 v[0:15], v[112:115], v[150:153], v[0:15]
	ds_read_b64_tr_b16 v[112:113], v207 offset:31744
	ds_read_b64_tr_b16 v[114:115], v207 offset:32256
	ds_read_b128 v[162:165], v206 offset:53248
	v_exp_f32_e32 v72, v72
	v_exp_f32_e32 v73, v73
	s_waitcnt lgkmcnt(7)
	v_mfma_f32_32x32x16_bf16 v[48:63], v[116:119], v[146:149], v[48:63]
	s_add_i32 m0, s22, 0x0
	s_addk_i32 m0, 0x400
	s_add_u32 s100, s100, 0x58000
	s_addc_u32 s101, s101, 0
	global_load_lds_dwordx4 v201, s[100:101]
	v_exp_f32_e32 v74, v74
	v_exp_f32_e32 v75, v75
	v_mfma_f32_32x32x16_bf16 v[32:47], v[104:107], v[146:149], v[32:47]
	v_exp_f32_e32 v76, v76
	v_exp_f32_e32 v77, v77
	s_waitcnt lgkmcnt(1)
	v_mfma_f32_32x32x16_bf16 v[16:31], v[108:111], v[146:149], v[16:31]
	v_exp_f32_e32 v78, v78
	v_exp_f32_e32 v79, v79
	v_mfma_f32_32x32x16_bf16 v[0:15], v[112:115], v[146:149], v[0:15]
	s_waitcnt vmcnt(8) lgkmcnt(0)
	s_barrier
	s_cmp_ge_u32 s24, s4
	s_mov_b32 s33, s24
	s_cbranch_scc1 .Lattn_done
	s_add_i32 s24, s33, 2
	v_mfma_f32_32x32x16_bf16 v[112:127], v[100:103], v[130:133], 0
	v_add_f32_e32 v100, v82, v80
	v_add_f32_e32 v101, v83, v81
	v_cvt_pk_bf16_f32 v158, v80, v81
	v_cvt_pk_bf16_f32 v159, v82, v83
	v_add_f32_e32 v80, v84, v100
	v_add_f32_e32 v81, v85, v101
	v_add_f32_e32 v146, v86, v80
	v_cvt_pk_bf16_f32 v160, v84, v85
	v_mfma_f32_32x32x16_bf16 v[96:111], v[96:99], v[130:133], 0
	v_add_f32_e32 v84, v87, v81
	v_cvt_pk_bf16_f32 v161, v86, v87
	ds_read_b64_tr_b16 v[80:81], v207 offset:32768
	ds_read_b64_tr_b16 v[82:83], v207 offset:33280
	v_add_f32_e32 v85, v88, v146
	v_add_f32_e32 v84, v89, v84
	v_mfma_f32_32x32x16_bf16 v[112:127], v[182:185], v[134:137], v[112:127]
	v_add_f32_e32 v146, v90, v85
	v_add_f32_e32 v147, v91, v84
	v_cvt_pk_bf16_f32 v154, v88, v89
	v_cvt_pk_bf16_f32 v155, v90, v91
	ds_read_b64_tr_b16 v[84:85], v207 offset:36864
	ds_read_b64_tr_b16 v[86:87], v207 offset:37376
	v_add_f32_e32 v88, v92, v146
	v_add_f32_e32 v89, v93, v147
	v_mfma_f32_32x32x16_bf16 v[96:111], v[178:181], v[134:137], v[96:111]
	v_add_f32_e32 v146, v94, v88
	v_add_f32_e32 v147, v95, v89
	v_cvt_pk_bf16_f32 v156, v92, v93
	v_cvt_pk_bf16_f32 v157, v94, v95
	ds_read_b64_tr_b16 v[88:89], v207 offset:40960
	ds_read_b64_tr_b16 v[90:91], v207 offset:41472
	v_add_f32_e32 v92, v64, v146
	v_add_f32_e32 v93, v65, v147
	v_mfma_f32_32x32x16_bf16 v[112:127], v[174:177], v[138:141], v[112:127]
	v_add_f32_e32 v92, v66, v92
	v_add_f32_e32 v93, v67, v93
	v_cvt_pk_bf16_f32 v150, v64, v65
	v_cvt_pk_bf16_f32 v151, v66, v67
	ds_read_b64_tr_b16 v[64:65], v207 offset:45056
	ds_read_b64_tr_b16 v[66:67], v207 offset:45568
	v_add_f32_e32 v92, v68, v92
	v_add_f32_e32 v93, v69, v93
	v_mfma_f32_32x32x16_bf16 v[96:111], v[170:173], v[138:141], v[96:111]
	s_min_u32 s90, s10, s23
	s_add_i32 s10, s10, 0x160000
	s_add_i32 m0, s5, 0xc000
	s_add_u32 s100, s44, s90
	s_addc_u32 s101, s45, 0
	global_load_lds_dwordx4 v199, s[100:101]
	v_add_f32_e32 v92, v70, v92
	v_add_f32_e32 v93, v71, v93
	v_cvt_pk_bf16_f32 v152, v68, v69
	v_cvt_pk_bf16_f32 v153, v70, v71
	v_add_f32_e32 v68, v72, v92
	v_add_f32_e32 v69, v73, v93
	v_mfma_f32_32x32x16_bf16 v[112:127], v[166:169], v[142:145], v[112:127]
	s_add_i32 m0, s32, 0xc000
	s_nop 0
	global_load_lds_dwordx4 v199, s[100:101] offset:128
	v_add_f32_e32 v68, v74, v68
	v_add_f32_e32 v69, v75, v69
	v_cvt_pk_bf16_f32 v146, v72, v73
	v_cvt_pk_bf16_f32 v147, v74, v75
	v_add_f32_e32 v68, v76, v68
	v_add_f32_e32 v69, v77, v69
	v_mfma_f32_32x32x16_bf16 v[96:111], v[162:165], v[142:145], v[96:111]
	s_min_u32 s90, s11, s23
	s_add_i32 s11, s11, 0x160000
	s_add_i32 m0, s22, 0x4000
	s_add_u32 s100, s44, s90
	s_addc_u32 s101, s45, 0
	global_load_lds_dwordx4 v201, s[100:101]
	v_add_f32_e32 v68, v78, v68
	v_add_f32_e32 v69, v79, v69
	v_cvt_pk_bf16_f32 v148, v76, v77
	v_cvt_pk_bf16_f32 v149, v78, v79
	s_nop 0
	v_exp_f32_e32 v112, v112
	v_exp_f32_e32 v113, v113
	s_waitcnt lgkmcnt(4)
	v_mfma_f32_32x32x16_bf16 v[48:63], v[80:83], v[158:161], v[48:63]
	v_add_f32_e32 v92, v68, v69
	ds_read_b64_tr_b16 v[68:69], v207 offset:33792
	ds_read_b64_tr_b16 v[70:71], v207 offset:34304
	v_exp_f32_e32 v114, v114
	v_exp_f32_e32 v115, v115
	v_mfma_f32_32x32x16_bf16 v[32:47], v[84:87], v[158:161], v[32:47]
	ds_read_b64_tr_b16 v[72:73], v207 offset:37888
	ds_read_b64_tr_b16 v[74:75], v207 offset:38400
	v_exp_f32_e32 v116, v116
	v_exp_f32_e32 v117, v117
	s_waitcnt lgkmcnt(4)
	v_mfma_f32_32x32x16_bf16 v[16:31], v[88:91], v[158:161], v[16:31]
	ds_read_b64_tr_b16 v[76:77], v207 offset:41984
	ds_read_b64_tr_b16 v[78:79], v207 offset:42496
	v_exp_f32_e32 v118, v118
	v_exp_f32_e32 v119, v119
	v_mfma_f32_32x32x16_bf16 v[0:15], v[64:67], v[158:161], v[0:15]
	ds_read_b64_tr_b16 v[80:81], v207 offset:46080
	ds_read_b64_tr_b16 v[82:83], v207 offset:46592
	v_exp_f32_e32 v120, v120
	v_exp_f32_e32 v121, v121
	s_waitcnt lgkmcnt(4)
	v_mfma_f32_32x32x16_bf16 v[48:63], v[68:71], v[154:157], v[48:63]
	ds_read_b64_tr_b16 v[84:85], v207 offset:34816
	ds_read_b64_tr_b16 v[86:87], v207 offset:35328
	ds_read_b128 v[68:71], v204
	v_exp_f32_e32 v122, v122
	v_exp_f32_e32 v123, v123
	v_mfma_f32_32x32x16_bf16 v[32:47], v[72:75], v[154:157], v[32:47]
	ds_read_b64_tr_b16 v[72:73], v207 offset:38912
	ds_read_b64_tr_b16 v[74:75], v207 offset:39424
	ds_read_b128 v[64:67], v204 offset:4096
	v_exp_f32_e32 v124, v124
	v_exp_f32_e32 v125, v125
	s_waitcnt lgkmcnt(6)
	v_mfma_f32_32x32x16_bf16 v[16:31], v[76:79], v[154:157], v[16:31]
	ds_read_b64_tr_b16 v[76:77], v207 offset:43008
	ds_read_b64_tr_b16 v[78:79], v207 offset:43520
	ds_read_b128 v[182:185], v128
	v_exp_f32_e32 v126, v126
	v_exp_f32_e32 v127, v127
	v_mfma_f32_32x32x16_bf16 v[0:15], v[80:83], v[154:157], v[0:15]
	ds_read_b64_tr_b16 v[80:81], v207 offset:47104
	ds_read_b64_tr_b16 v[82:83], v207 offset:47616
	ds_read_b128 v[178:181], v128 offset:4096
	v_exp_f32_e32 v96, v96
	v_exp_f32_e32 v97, v97
	s_waitcnt lgkmcnt(7)
	v_mfma_f32_32x32x16_bf16 v[48:63], v[84:87], v[150:153], v[48:63]
	ds_read_b64_tr_b16 v[84:85], v207 offset:35840
	ds_read_b64_tr_b16 v[86:87], v207 offset:36352
	ds_read_b128 v[174:177], v205
	v_exp_f32_e32 v98, v98
	v_exp_f32_e32 v99, v99
	v_mfma_f32_32x32x16_bf16 v[32:47], v[72:75], v[150:153], v[32:47]
	ds_read_b64_tr_b16 v[72:73], v207 offset:39936
	ds_read_b64_tr_b16 v[74:75], v207 offset:40448
	ds_read_b128 v[170:173], v205 offset:4096
	v_exp_f32_e32 v100, v100
	v_exp_f32_e32 v101, v101
	s_waitcnt lgkmcnt(7)
	v_mfma_f32_32x32x16_bf16 v[16:31], v[76:79], v[150:153], v[16:31]
	ds_read_b64_tr_b16 v[76:77], v207 offset:44032
	ds_read_b64_tr_b16 v[78:79], v207 offset:44544
	ds_read_b128 v[166:169], v206
	v_exp_f32_e32 v102, v102
	v_exp_f32_e32 v103, v103
	v_mfma_f32_32x32x16_bf16 v[0:15], v[80:83], v[150:153], v[0:15]
	ds_read_b64_tr_b16 v[80:81], v207 offset:48128
	ds_read_b64_tr_b16 v[82:83], v207 offset:48640
	ds_read_b128 v[162:165], v206 offset:4096
	v_exp_f32_e32 v104, v104
	v_exp_f32_e32 v105, v105
	s_waitcnt lgkmcnt(7)
	v_mfma_f32_32x32x16_bf16 v[48:63], v[84:87], v[146:149], v[48:63]
	s_add_i32 m0, s22, 0x4000
	s_addk_i32 m0, 0x400
	s_add_u32 s100, s100, 0x58000
	s_addc_u32 s101, s101, 0
	global_load_lds_dwordx4 v201, s[100:101]
	v_exp_f32_e32 v106, v106
	v_exp_f32_e32 v107, v107
	v_mfma_f32_32x32x16_bf16 v[32:47], v[72:75], v[146:149], v[32:47]
	v_exp_f32_e32 v108, v108
	v_exp_f32_e32 v109, v109
	s_waitcnt lgkmcnt(1)
	v_mfma_f32_32x32x16_bf16 v[16:31], v[76:79], v[146:149], v[16:31]
	v_exp_f32_e32 v110, v110
	v_exp_f32_e32 v111, v111
	v_mfma_f32_32x32x16_bf16 v[0:15], v[80:83], v[146:149], v[0:15]
	s_waitcnt vmcnt(8) lgkmcnt(0)
	s_barrier
	v_add_f32_e32 v186, v209, v92
	v_mfma_f32_32x32x16_bf16 v[80:95], v[68:71], v[130:133], 0
	v_add_f32_e32 v68, v114, v112
	v_add_f32_e32 v69, v115, v113
	v_cvt_pk_bf16_f32 v158, v112, v113
	v_cvt_pk_bf16_f32 v159, v114, v115
	v_add_f32_e32 v68, v116, v68
	v_add_f32_e32 v112, v117, v69
	v_add_f32_e32 v146, v118, v68
	v_cvt_pk_bf16_f32 v160, v116, v117
	v_mfma_f32_32x32x16_bf16 v[64:79], v[64:67], v[130:133], 0
	v_add_f32_e32 v116, v119, v112
	v_cvt_pk_bf16_f32 v161, v118, v119
	ds_read_b64_tr_b16 v[112:113], v207 offset:49152
	ds_read_b64_tr_b16 v[114:115], v207 offset:49664
	v_add_f32_e32 v117, v120, v146
	v_add_f32_e32 v116, v121, v116
	v_mfma_f32_32x32x16_bf16 v[80:95], v[182:185], v[134:137], v[80:95]
	v_add_f32_e32 v146, v122, v117
	v_add_f32_e32 v147, v123, v116
	v_cvt_pk_bf16_f32 v154, v120, v121
	v_cvt_pk_bf16_f32 v155, v122, v123
	ds_read_b64_tr_b16 v[116:117], v207 offset:53248
	ds_read_b64_tr_b16 v[118:119], v207 offset:53760
	v_add_f32_e32 v120, v124, v146
	v_add_f32_e32 v121, v125, v147
	v_mfma_f32_32x32x16_bf16 v[64:79], v[178:181], v[134:137], v[64:79]
	v_add_f32_e32 v146, v126, v120
	v_add_f32_e32 v147, v127, v121
	v_cvt_pk_bf16_f32 v156, v124, v125
	v_cvt_pk_bf16_f32 v157, v126, v127
	ds_read_b64_tr_b16 v[120:121], v207 offset:57344
	ds_read_b64_tr_b16 v[122:123], v207 offset:57856
	v_add_f32_e32 v124, v96, v146
	v_add_f32_e32 v125, v97, v147
	v_mfma_f32_32x32x16_bf16 v[80:95], v[174:177], v[138:141], v[80:95]
	v_add_f32_e32 v124, v98, v124
	v_add_f32_e32 v125, v99, v125
	v_cvt_pk_bf16_f32 v150, v96, v97
	v_cvt_pk_bf16_f32 v151, v98, v99
	ds_read_b64_tr_b16 v[96:97], v207 offset:61440
	ds_read_b64_tr_b16 v[98:99], v207 offset:61952
	v_add_f32_e32 v124, v100, v124
	v_add_f32_e32 v125, v101, v125
	v_mfma_f32_32x32x16_bf16 v[64:79], v[170:173], v[138:141], v[64:79]
	s_min_u32 s90, s10, s23
	s_add_i32 s10, s10, 0x160000
	s_add_i32 m0, s5, 0x0
	s_add_u32 s100, s44, s90
	s_addc_u32 s101, s45, 0
	global_load_lds_dwordx4 v199, s[100:101]
	v_add_f32_e32 v124, v102, v124
	v_add_f32_e32 v125, v103, v125
	v_cvt_pk_bf16_f32 v152, v100, v101
	v_cvt_pk_bf16_f32 v153, v102, v103
	v_add_f32_e32 v100, v104, v124
	v_add_f32_e32 v101, v105, v125
	v_mfma_f32_32x32x16_bf16 v[80:95], v[166:169], v[142:145], v[80:95]
	s_add_i32 m0, s32, 0x0
	s_nop 0
	global_load_lds_dwordx4 v199, s[100:101] offset:128
	v_add_f32_e32 v100, v106, v100
	v_add_f32_e32 v101, v107, v101
	v_cvt_pk_bf16_f32 v146, v104, v105
	v_cvt_pk_bf16_f32 v147, v106, v107
	v_add_f32_e32 v100, v108, v100
	v_add_f32_e32 v101, v109, v101
	v_mfma_f32_32x32x16_bf16 v[64:79], v[162:165], v[142:145], v[64:79]
	s_min_u32 s90, s11, s23
	s_add_i32 s11, s11, 0x160000
	s_add_i32 m0, s22, 0x8000
	s_add_u32 s100, s44, s90
	s_addc_u32 s101, s45, 0
	global_load_lds_dwordx4 v201, s[100:101]
	v_add_f32_e32 v100, v110, v100
	v_add_f32_e32 v101, v111, v101
	v_cvt_pk_bf16_f32 v148, v108, v109
	v_cvt_pk_bf16_f32 v149, v110, v111
	v_add_f32_e32 v100, v100, v101
	v_exp_f32_e32 v80, v80
	v_exp_f32_e32 v81, v81
	s_waitcnt lgkmcnt(4)
	v_mfma_f32_32x32x16_bf16 v[48:63], v[112:115], v[158:161], v[48:63]
	v_add_f32_e32 v209, v186, v100
	ds_read_b64_tr_b16 v[100:101], v207 offset:50176
	ds_read_b64_tr_b16 v[102:103], v207 offset:50688
	v_exp_f32_e32 v82, v82
	v_exp_f32_e32 v83, v83
	v_mfma_f32_32x32x16_bf16 v[32:47], v[116:119], v[158:161], v[32:47]
	ds_read_b64_tr_b16 v[104:105], v207 offset:54272
	ds_read_b64_tr_b16 v[106:107], v207 offset:54784
	v_exp_f32_e32 v84, v84
	v_exp_f32_e32 v85, v85
	s_waitcnt lgkmcnt(4)
	v_mfma_f32_32x32x16_bf16 v[16:31], v[120:123], v[158:161], v[16:31]
	ds_read_b64_tr_b16 v[108:109], v207 offset:58368
	ds_read_b64_tr_b16 v[110:111], v207 offset:58880
	v_exp_f32_e32 v86, v86
	v_exp_f32_e32 v87, v87
	v_mfma_f32_32x32x16_bf16 v[0:15], v[96:99], v[158:161], v[0:15]
	ds_read_b64_tr_b16 v[112:113], v207 offset:62464
	ds_read_b64_tr_b16 v[114:115], v207 offset:62976
	v_exp_f32_e32 v88, v88
	v_exp_f32_e32 v89, v89
	s_waitcnt lgkmcnt(4)
	v_mfma_f32_32x32x16_bf16 v[48:63], v[100:103], v[154:157], v[48:63]
	ds_read_b64_tr_b16 v[116:117], v207 offset:51200
	ds_read_b64_tr_b16 v[118:119], v207 offset:51712
	ds_read_b128 v[100:103], v204 offset:16384
	v_exp_f32_e32 v90, v90
	v_exp_f32_e32 v91, v91
	v_mfma_f32_32x32x16_bf16 v[32:47], v[104:107], v[154:157], v[32:47]
	ds_read_b64_tr_b16 v[104:105], v207 offset:55296
	ds_read_b64_tr_b16 v[106:107], v207 offset:55808
	ds_read_b128 v[96:99], v204 offset:20480
	v_exp_f32_e32 v92, v92
	v_exp_f32_e32 v93, v93
	s_waitcnt lgkmcnt(6)
	v_mfma_f32_32x32x16_bf16 v[16:31], v[108:111], v[154:157], v[16:31]
	ds_read_b64_tr_b16 v[108:109], v207 offset:59392
	ds_read_b64_tr_b16 v[110:111], v207 offset:59904
	ds_read_b128 v[182:185], v128 offset:16384
	v_exp_f32_e32 v94, v94
	v_exp_f32_e32 v95, v95
	v_mfma_f32_32x32x16_bf16 v[0:15], v[112:115], v[154:157], v[0:15]
	ds_read_b64_tr_b16 v[112:113], v207 offset:63488
	ds_read_b64_tr_b16 v[114:115], v207 offset:64000
	ds_read_b128 v[178:181], v128 offset:20480
	v_exp_f32_e32 v64, v64
	v_exp_f32_e32 v65, v65
	s_waitcnt lgkmcnt(7)
	v_mfma_f32_32x32x16_bf16 v[48:63], v[116:119], v[150:153], v[48:63]
	ds_read_b64_tr_b16 v[116:117], v207 offset:52224
	ds_read_b64_tr_b16 v[118:119], v207 offset:52736
	ds_read_b128 v[174:177], v205 offset:16384
	v_exp_f32_e32 v66, v66
	v_exp_f32_e32 v67, v67
	v_mfma_f32_32x32x16_bf16 v[32:47], v[104:107], v[150:153], v[32:47]
	ds_read_b64_tr_b16 v[104:105], v207 offset:56320
	ds_read_b64_tr_b16 v[106:107], v207 offset:56832
	ds_read_b128 v[170:173], v205 offset:20480
	v_exp_f32_e32 v68, v68
	v_exp_f32_e32 v69, v69
	s_waitcnt lgkmcnt(7)
	v_mfma_f32_32x32x16_bf16 v[16:31], v[108:111], v[150:153], v[16:31]
	ds_read_b64_tr_b16 v[108:109], v207 offset:60416
	ds_read_b64_tr_b16 v[110:111], v207 offset:60928
	ds_read_b128 v[166:169], v206 offset:16384
	v_exp_f32_e32 v70, v70
	v_exp_f32_e32 v71, v71
	v_mfma_f32_32x32x16_bf16 v[0:15], v[112:115], v[150:153], v[0:15]
	ds_read_b64_tr_b16 v[112:113], v207 offset:64512
	ds_read_b64_tr_b16 v[114:115], v207 offset:65024
	ds_read_b128 v[162:165], v206 offset:20480
	v_exp_f32_e32 v72, v72
	v_exp_f32_e32 v73, v73
	s_waitcnt lgkmcnt(7)
	v_mfma_f32_32x32x16_bf16 v[48:63], v[116:119], v[146:149], v[48:63]
	s_add_i32 m0, s22, 0x8000
	s_addk_i32 m0, 0x400
	s_add_u32 s100, s100, 0x58000
	s_addc_u32 s101, s101, 0
	global_load_lds_dwordx4 v201, s[100:101]
	v_exp_f32_e32 v74, v74
	v_exp_f32_e32 v75, v75
	v_mfma_f32_32x32x16_bf16 v[32:47], v[104:107], v[146:149], v[32:47]
	v_exp_f32_e32 v76, v76
	v_exp_f32_e32 v77, v77
	s_waitcnt lgkmcnt(1)
	v_mfma_f32_32x32x16_bf16 v[16:31], v[108:111], v[146:149], v[16:31]
	v_exp_f32_e32 v78, v78
	v_exp_f32_e32 v79, v79
	v_mfma_f32_32x32x16_bf16 v[0:15], v[112:115], v[146:149], v[0:15]
	s_waitcnt vmcnt(8) lgkmcnt(0)
	s_barrier
	s_cmp_ge_u32 s24, s4
	s_mov_b32 s33, s24
	s_cbranch_scc0 .LBB0_86
